# GEMM K-loops: interleaved fragment reads, ds_write+load pairs in last MFMA group (start 24), exact counted waits, hoisted prelude; XSS overlap
# baseline (speedup 1.0000x reference)
; #define MFMA32(a, b, c) __builtin_amdgcn_mfma_f32_32x32x16_bf16((a), (b), (c), 0, 0, 0)
; #define G_LOAD(KT) do { const int k0_ = (KT) << 6; _Pragma("unroll") for (int p = 0; p < 4; ++p) { \
;     ra[p] = *(const u32x4*)(ap + (size_t)(64 * p) * lda + k0_); rb[p] = *(const u32x4*)(bp + (size_t)(64 * p) * ldb + k0_); } } while (0)
; template <bool SWAP, bool SSQ, bool ZERO = true>
; DI void gemm_main(const u16* __restrict__ A, int lda, const u16* __restrict__ Bt, int ldb, int K, char* lds,
;                   f32x16 (&acc)[4][2], float* rs_lds) {
;     ...
;   for (int kt = 0; kt < nk; ++kt) {
;     const int st = (kt & 1) * 2 * G_TILE;
;     {
;       bf16x8 fa[2][4], fb[2][2];
; #pragma unroll
;       for (int i = 0; i < 4; ++i) fa[0][i] = *(const bf16x8*)(abase + st + i * 32 * GS);
; #pragma unroll
;       for (int i = 0; i < 2; ++i) fb[0][i] = *(const bf16x8*)(bbase + st + i * 32 * GS);
; #pragma unroll
;       for (int ks = 0; ks < 4; ++ks) {
;         if (ks + 1 < 4) {
; #pragma unroll
;           for (int i = 0; i < 4; ++i) fa[(ks + 1) & 1][i] = *(const bf16x8*)(abase + st + i * 32 * GS + (ks + 1) * 32);
; #pragma unroll
;           for (int i = 0; i < 2; ++i) fb[(ks + 1) & 1][i] = *(const bf16x8*)(bbase + st + i * 32 * GS + (ks + 1) * 32);
;         }
;         __builtin_amdgcn_sched_barrier(0);
;         __builtin_amdgcn_s_setprio(1);
; #pragma unroll
;         for (int mt = 0; mt < 4; ++mt)
; #pragma unroll
;           for (int nt = 0; nt < 2; ++nt)
;             acc[mt][nt] = SWAP ? MFMA32(fb[ks & 1][nt], fa[ks & 1][mt], acc[mt][nt]) : MFMA32(fa[ks & 1][mt], fb[ks & 1][nt], acc[mt][nt]);
;         __builtin_amdgcn_s_setprio(0);
;         __builtin_amdgcn_sched_barrier(0);
;       }
;     }
;     if (kt + 1 < nk) G_WRITE((kt + 1) & 1);
;     if (kt + 2 < nk) G_LOAD(kt + 2);
;     __syncthreads();
;   }
.LBB0_92:
	s_cmp_gt_u32 s52, 29
	s_cbranch_scc1 .Lg92_tail
	ds_read_b128 v[204:207], v165 offset:36864
	ds_read_b128 v[172:175], v0
	ds_read_b128 v[212:215], v165 offset:41472
	ds_read_b128 v[180:183], v0 offset:4608
	ds_read_b128 v[188:191], v0 offset:9216
	ds_read_b128 v[196:199], v0 offset:13824
	s_setprio 1
	s_waitcnt lgkmcnt(4)
	v_mfma_f32_32x32x16_bf16 v[114:129], v[204:207], v[172:175], v[114:129]
	ds_read_b128 v[208:211], v165 offset:36896
	s_waitcnt lgkmcnt(4)
	v_mfma_f32_32x32x16_bf16 v[98:113], v[212:215], v[172:175], v[98:113]
	ds_read_b128 v[176:179], v0 offset:32
	ds_read_b128 v[172:175], v0 offset:64
	s_waitcnt lgkmcnt(5)
	v_mfma_f32_32x32x16_bf16 v[82:97], v[204:207], v[180:183], v[82:97]
	ds_read_b128 v[216:219], v165 offset:41504
	v_mfma_f32_32x32x16_bf16 v[66:81], v[212:215], v[180:183], v[66:81]
	ds_read_b128 v[184:187], v0 offset:4640
	ds_read_b128 v[180:183], v0 offset:4672
	s_waitcnt lgkmcnt(7)
	v_mfma_f32_32x32x16_bf16 v[50:65], v[204:207], v[188:191], v[50:65]
	ds_read_b128 v[192:195], v0 offset:9248
	v_mfma_f32_32x32x16_bf16 v[34:49], v[212:215], v[188:191], v[34:49]
	ds_read_b128 v[200:203], v0 offset:13856
	ds_read_b128 v[188:191], v0 offset:9280
	s_waitcnt lgkmcnt(9)
	v_mfma_f32_32x32x16_bf16 v[18:33], v[204:207], v[196:199], v[18:33]
	ds_read_b128 v[204:207], v165 offset:36928
	v_mfma_f32_32x32x16_bf16 v[2:17], v[212:215], v[196:199], v[2:17]
	ds_read_b128 v[212:215], v165 offset:41536
	ds_read_b128 v[196:199], v0 offset:13888
	s_setprio 0
	s_setprio 1
	s_waitcnt lgkmcnt(10)
	v_mfma_f32_32x32x16_bf16 v[114:129], v[208:211], v[176:179], v[114:129]
	s_waitcnt lgkmcnt(8)
	v_mfma_f32_32x32x16_bf16 v[98:113], v[216:219], v[176:179], v[98:113]
	ds_read_b128 v[176:179], v0 offset:96
	s_waitcnt lgkmcnt(8)
	v_mfma_f32_32x32x16_bf16 v[82:97], v[208:211], v[184:187], v[82:97]
	v_mfma_f32_32x32x16_bf16 v[66:81], v[216:219], v[184:187], v[66:81]
	ds_read_b128 v[184:187], v0 offset:4704
	s_waitcnt lgkmcnt(7)
	v_mfma_f32_32x32x16_bf16 v[50:65], v[208:211], v[192:195], v[50:65]
	v_mfma_f32_32x32x16_bf16 v[34:49], v[216:219], v[192:195], v[34:49]
	ds_read_b128 v[192:195], v0 offset:9312
	s_waitcnt lgkmcnt(7)
	v_mfma_f32_32x32x16_bf16 v[18:33], v[208:211], v[200:203], v[18:33]
	ds_read_b128 v[208:211], v165 offset:36960
	v_mfma_f32_32x32x16_bf16 v[2:17], v[216:219], v[200:203], v[2:17]
	ds_read_b128 v[216:219], v165 offset:41568
	ds_read_b128 v[200:203], v0 offset:13920
	s_setprio 0
	s_setprio 1
	s_waitcnt lgkmcnt(8)
	v_mfma_f32_32x32x16_bf16 v[114:129], v[204:207], v[172:175], v[114:129]
	s_waitcnt lgkmcnt(7)
	v_mfma_f32_32x32x16_bf16 v[98:113], v[212:215], v[172:175], v[98:113]
	v_mfma_f32_32x32x16_bf16 v[82:97], v[204:207], v[180:183], v[82:97]
	v_mfma_f32_32x32x16_bf16 v[66:81], v[212:215], v[180:183], v[66:81]
	v_mfma_f32_32x32x16_bf16 v[50:65], v[204:207], v[188:191], v[50:65]
	v_mfma_f32_32x32x16_bf16 v[34:49], v[212:215], v[188:191], v[34:49]
	s_waitcnt lgkmcnt(6)
	v_mfma_f32_32x32x16_bf16 v[18:33], v[204:207], v[196:199], v[18:33]
	v_mfma_f32_32x32x16_bf16 v[2:17], v[212:215], v[196:199], v[2:17]
	s_setprio 0
	s_setprio 1
	s_and_b32 s62, s53, 2
	s_mul_i32 s62, s62, 0x9000
	v_add_u32_e32 v240, s62, v162
	v_lshl_add_u64 v[220:221], v[168:169], 0, s[86:87]
	v_lshl_add_u64 v[234:235], v[166:167], 0, s[86:87]
	s_waitcnt lgkmcnt(2)
	v_mfma_f32_32x32x16_bf16 v[114:129], v[208:211], v[176:179], v[114:129]
	s_waitcnt vmcnt(7)
	ds_write_b128 v240, v[130:133]
	global_load_dwordx4 v[130:133], v[220:221], off offset:256
	v_add_co_u32_e32 v220, vcc, 0x40000, v220
	s_waitcnt lgkmcnt(2)
	v_mfma_f32_32x32x16_bf16 v[98:113], v[216:219], v[176:179], v[98:113]
	s_waitcnt vmcnt(7)
	ds_write_b128 v240, v[134:137] offset:36864
	v_addc_co_u32_e32 v221, vcc, 0, v221, vcc
	global_load_dwordx4 v[134:137], v[234:235], off offset:256
	v_add_co_u32_e32 v234, vcc, 0x40000, v234
	v_mfma_f32_32x32x16_bf16 v[82:97], v[208:211], v[184:187], v[82:97]
	s_waitcnt vmcnt(7)
	ds_write_b128 v240, v[138:141] offset:9216
	v_addc_co_u32_e32 v235, vcc, 0, v235, vcc
	global_load_dwordx4 v[138:141], v[220:221], off offset:256
	v_add_co_u32_e32 v220, vcc, 0x40000, v220
	v_mfma_f32_32x32x16_bf16 v[66:81], v[216:219], v[184:187], v[66:81]
	s_waitcnt vmcnt(7)
	ds_write_b128 v240, v[142:145] offset:46080
	v_addc_co_u32_e32 v221, vcc, 0, v221, vcc
	global_load_dwordx4 v[142:145], v[234:235], off offset:256
	v_add_co_u32_e32 v234, vcc, 0x40000, v234
	v_mfma_f32_32x32x16_bf16 v[50:65], v[208:211], v[192:195], v[50:65]
	s_waitcnt vmcnt(7)
	ds_write_b128 v240, v[146:149] offset:18432
	v_addc_co_u32_e32 v235, vcc, 0, v235, vcc
	global_load_dwordx4 v[146:149], v[220:221], off offset:256
	v_add_co_u32_e32 v220, vcc, 0x40000, v220
	v_mfma_f32_32x32x16_bf16 v[34:49], v[216:219], v[192:195], v[34:49]
	s_waitcnt vmcnt(7)
	ds_write_b128 v240, v[150:153] offset:55296
	v_addc_co_u32_e32 v221, vcc, 0, v221, vcc
	global_load_dwordx4 v[150:153], v[234:235], off offset:256
	v_add_co_u32_e32 v234, vcc, 0x40000, v234
	s_waitcnt lgkmcnt(6)
	v_mfma_f32_32x32x16_bf16 v[18:33], v[208:211], v[200:203], v[18:33]
	s_waitcnt vmcnt(7)
	ds_write_b128 v240, v[154:157] offset:27648
	v_addc_co_u32_e32 v235, vcc, 0, v235, vcc
	global_load_dwordx4 v[154:157], v[220:221], off offset:256
	v_mfma_f32_32x32x16_bf16 v[2:17], v[216:219], v[200:203], v[2:17]
	s_waitcnt vmcnt(7)
	ds_write_b128 v240, v[158:161] offset:64512
	global_load_dwordx4 v[158:161], v[234:235], off offset:256
	s_setprio 0
	s_branch .LBB0_91

; #define MFMA32(a, b, c) __builtin_amdgcn_mfma_f32_32x32x16_bf16((a), (b), (c), 0, 0, 0)
; #define G_LOAD(KT) do { const int k0_ = (KT) << 6; _Pragma("unroll") for (int p = 0; p < 4; ++p) { \
;     ra[p] = *(const u32x4*)(ap + (size_t)(64 * p) * lda + k0_); rb[p] = *(const u32x4*)(bp + (size_t)(64 * p) * ldb + k0_); } } while (0)
; template <bool SWAP, bool SSQ, bool ZERO = true>
; DI void gemm_main(const u16* __restrict__ A, int lda, const u16* __restrict__ Bt, int ldb, int K, char* lds,
;                   f32x16 (&acc)[4][2], float* rs_lds) {
;     ...
;   for (int kt = 0; kt < nk; ++kt) {
;     const int st = (kt & 1) * 2 * G_TILE;
;     {
;       bf16x8 fa[2][4], fb[2][2];
; #pragma unroll
;       for (int i = 0; i < 4; ++i) fa[0][i] = *(const bf16x8*)(abase + st + i * 32 * GS);
; #pragma unroll
;       for (int i = 0; i < 2; ++i) fb[0][i] = *(const bf16x8*)(bbase + st + i * 32 * GS);
; #pragma unroll
;       for (int ks = 0; ks < 4; ++ks) {
;         if (ks + 1 < 4) {
; #pragma unroll
;           for (int i = 0; i < 4; ++i) fa[(ks + 1) & 1][i] = *(const bf16x8*)(abase + st + i * 32 * GS + (ks + 1) * 32);
; #pragma unroll
;           for (int i = 0; i < 2; ++i) fb[(ks + 1) & 1][i] = *(const bf16x8*)(bbase + st + i * 32 * GS + (ks + 1) * 32);
;         }
;         __builtin_amdgcn_sched_barrier(0);
;         __builtin_amdgcn_s_setprio(1);
; #pragma unroll
;         for (int mt = 0; mt < 4; ++mt)
; #pragma unroll
;           for (int nt = 0; nt < 2; ++nt)
;             acc[mt][nt] = SWAP ? MFMA32(fb[ks & 1][nt], fa[ks & 1][mt], acc[mt][nt]) : MFMA32(fa[ks & 1][mt], fb[ks & 1][nt], acc[mt][nt]);
;         __builtin_amdgcn_s_setprio(0);
;         __builtin_amdgcn_sched_barrier(0);
;       }
;     }
;     if (kt + 1 < nk) G_WRITE((kt + 1) & 1);
;     if (kt + 2 < nk) G_LOAD(kt + 2);
;     __syncthreads();
;   }
.LBB0_119:
	s_cmp_gt_u32 s2, 29
	s_cbranch_scc1 .Lg119_tail
	ds_read_b128 v[170:173], v0
	ds_read_b128 v[202:205], v165 offset:36864
	ds_read_b128 v[210:213], v165 offset:41472
	ds_read_b128 v[178:181], v0 offset:4608
	ds_read_b128 v[186:189], v0 offset:9216
	ds_read_b128 v[194:197], v0 offset:13824
	s_setprio 1
	s_waitcnt lgkmcnt(4)
	v_mfma_f32_32x32x16_bf16 v[114:129], v[170:173], v[202:205], v[114:129]
	ds_read_b128 v[174:177], v0 offset:32
	s_waitcnt lgkmcnt(4)
	v_mfma_f32_32x32x16_bf16 v[98:113], v[170:173], v[210:213], v[98:113]
	ds_read_b128 v[206:209], v165 offset:36896
	ds_read_b128 v[170:173], v0 offset:64
	s_waitcnt lgkmcnt(5)
	v_mfma_f32_32x32x16_bf16 v[82:97], v[178:181], v[202:205], v[82:97]
	ds_read_b128 v[214:217], v165 offset:41504
	v_mfma_f32_32x32x16_bf16 v[66:81], v[178:181], v[210:213], v[66:81]
	ds_read_b128 v[182:185], v0 offset:4640
	ds_read_b128 v[178:181], v0 offset:4672
	s_waitcnt lgkmcnt(7)
	v_mfma_f32_32x32x16_bf16 v[50:65], v[186:189], v[202:205], v[50:65]
	ds_read_b128 v[190:193], v0 offset:9248
	v_mfma_f32_32x32x16_bf16 v[34:49], v[186:189], v[210:213], v[34:49]
	ds_read_b128 v[198:201], v0 offset:13856
	ds_read_b128 v[186:189], v0 offset:9280
	s_waitcnt lgkmcnt(9)
	v_mfma_f32_32x32x16_bf16 v[18:33], v[194:197], v[202:205], v[18:33]
	ds_read_b128 v[202:205], v165 offset:36928
	v_mfma_f32_32x32x16_bf16 v[2:17], v[194:197], v[210:213], v[2:17]
	ds_read_b128 v[210:213], v165 offset:41536
	ds_read_b128 v[194:197], v0 offset:13888
	s_setprio 0
	s_setprio 1
	s_waitcnt lgkmcnt(10)
	v_mfma_f32_32x32x16_bf16 v[114:129], v[174:177], v[206:209], v[114:129]
	s_waitcnt lgkmcnt(8)
	v_mfma_f32_32x32x16_bf16 v[98:113], v[174:177], v[214:217], v[98:113]
	ds_read_b128 v[174:177], v0 offset:96
	s_waitcnt lgkmcnt(8)
	v_mfma_f32_32x32x16_bf16 v[82:97], v[182:185], v[206:209], v[82:97]
	v_mfma_f32_32x32x16_bf16 v[66:81], v[182:185], v[214:217], v[66:81]
	ds_read_b128 v[182:185], v0 offset:4704
	s_waitcnt lgkmcnt(7)
	v_mfma_f32_32x32x16_bf16 v[50:65], v[190:193], v[206:209], v[50:65]
	v_mfma_f32_32x32x16_bf16 v[34:49], v[190:193], v[214:217], v[34:49]
	ds_read_b128 v[190:193], v0 offset:9312
	s_waitcnt lgkmcnt(7)
	v_mfma_f32_32x32x16_bf16 v[18:33], v[198:201], v[206:209], v[18:33]
	ds_read_b128 v[206:209], v165 offset:36960
	v_mfma_f32_32x32x16_bf16 v[2:17], v[198:201], v[214:217], v[2:17]
	ds_read_b128 v[214:217], v165 offset:41568
	ds_read_b128 v[198:201], v0 offset:13920
	s_setprio 0
	s_setprio 1
	s_waitcnt lgkmcnt(8)
	v_mfma_f32_32x32x16_bf16 v[114:129], v[170:173], v[202:205], v[114:129]
	s_waitcnt lgkmcnt(7)
	v_mfma_f32_32x32x16_bf16 v[98:113], v[170:173], v[210:213], v[98:113]
	v_mfma_f32_32x32x16_bf16 v[82:97], v[178:181], v[202:205], v[82:97]
	v_mfma_f32_32x32x16_bf16 v[66:81], v[178:181], v[210:213], v[66:81]
	v_mfma_f32_32x32x16_bf16 v[50:65], v[186:189], v[202:205], v[50:65]
	v_mfma_f32_32x32x16_bf16 v[34:49], v[186:189], v[210:213], v[34:49]
	s_waitcnt lgkmcnt(6)
	v_mfma_f32_32x32x16_bf16 v[18:33], v[194:197], v[202:205], v[18:33]
	v_mfma_f32_32x32x16_bf16 v[2:17], v[194:197], v[210:213], v[2:17]
	s_setprio 0
	s_setprio 1
	s_and_b32 s52, s4, 2
	s_mul_i32 s52, s52, 0x9000
	v_add_u32_e32 v240, s52, v162
	v_lshl_add_u64 v[220:221], v[168:169], 0, s[0:1]
	v_lshl_add_u64 v[234:235], v[166:167], 0, s[0:1]
	s_waitcnt lgkmcnt(2)
	v_mfma_f32_32x32x16_bf16 v[114:129], v[174:177], v[206:209], v[114:129]
	s_waitcnt vmcnt(7)
	ds_write_b128 v240, v[130:133]
	global_load_dwordx4 v[130:133], v[220:221], off offset:256
	v_add_co_u32_e32 v220, vcc, 0x40000, v220
	s_waitcnt lgkmcnt(2)
	v_mfma_f32_32x32x16_bf16 v[98:113], v[174:177], v[214:217], v[98:113]
	s_waitcnt vmcnt(7)
	ds_write_b128 v240, v[134:137] offset:36864
	v_addc_co_u32_e32 v221, vcc, 0, v221, vcc
	global_load_dwordx4 v[134:137], v[234:235], off offset:256
	v_add_co_u32_e32 v234, vcc, 0x40000, v234
	v_mfma_f32_32x32x16_bf16 v[82:97], v[182:185], v[206:209], v[82:97]
	s_waitcnt vmcnt(7)
	ds_write_b128 v240, v[138:141] offset:9216
	v_addc_co_u32_e32 v235, vcc, 0, v235, vcc
	global_load_dwordx4 v[138:141], v[220:221], off offset:256
	v_add_co_u32_e32 v220, vcc, 0x40000, v220
	v_mfma_f32_32x32x16_bf16 v[66:81], v[182:185], v[214:217], v[66:81]
	s_waitcnt vmcnt(7)
	ds_write_b128 v240, v[142:145] offset:46080
	v_addc_co_u32_e32 v221, vcc, 0, v221, vcc
	global_load_dwordx4 v[142:145], v[234:235], off offset:256
	v_add_co_u32_e32 v234, vcc, 0x40000, v234
	v_mfma_f32_32x32x16_bf16 v[50:65], v[190:193], v[206:209], v[50:65]
	s_waitcnt vmcnt(7)
	ds_write_b128 v240, v[146:149] offset:18432
	v_addc_co_u32_e32 v235, vcc, 0, v235, vcc
	global_load_dwordx4 v[146:149], v[220:221], off offset:256
	v_add_co_u32_e32 v220, vcc, 0x40000, v220
	v_mfma_f32_32x32x16_bf16 v[34:49], v[190:193], v[214:217], v[34:49]
	s_waitcnt vmcnt(7)
	ds_write_b128 v240, v[150:153] offset:55296
	v_addc_co_u32_e32 v221, vcc, 0, v221, vcc
	global_load_dwordx4 v[150:153], v[234:235], off offset:256
	v_add_co_u32_e32 v234, vcc, 0x40000, v234
	s_waitcnt lgkmcnt(6)
	v_mfma_f32_32x32x16_bf16 v[18:33], v[198:201], v[206:209], v[18:33]
	s_waitcnt vmcnt(7)
	ds_write_b128 v240, v[154:157] offset:27648
	v_addc_co_u32_e32 v235, vcc, 0, v235, vcc
	global_load_dwordx4 v[154:157], v[220:221], off offset:256
	v_mfma_f32_32x32x16_bf16 v[2:17], v[198:201], v[214:217], v[2:17]
	s_waitcnt vmcnt(7)
	ds_write_b128 v240, v[158:161] offset:64512
	global_load_dwordx4 v[158:161], v[234:235], off offset:256
	s_setprio 0
	s_branch .LBB0_118

; #define MFMA32(a, b, c) __builtin_amdgcn_mfma_f32_32x32x16_bf16((a), (b), (c), 0, 0, 0)
; #define G_LOAD(KT) do { const int k0_ = (KT) << 6; _Pragma("unroll") for (int p = 0; p < 4; ++p) { \
;     ra[p] = *(const u32x4*)(ap + (size_t)(64 * p) * lda + k0_); rb[p] = *(const u32x4*)(bp + (size_t)(64 * p) * ldb + k0_); } } while (0)
; template <bool SWAP, bool SSQ, bool ZERO = true>
; DI void gemm_main(const u16* __restrict__ A, int lda, const u16* __restrict__ Bt, int ldb, int K, char* lds,
;                   f32x16 (&acc)[4][2], float* rs_lds) {
;     ...
;   for (int kt = 0; kt < nk; ++kt) {
;     const int st = (kt & 1) * 2 * G_TILE;
;     {
;       bf16x8 fa[2][4], fb[2][2];
; #pragma unroll
;       for (int i = 0; i < 4; ++i) fa[0][i] = *(const bf16x8*)(abase + st + i * 32 * GS);
; #pragma unroll
;       for (int i = 0; i < 2; ++i) fb[0][i] = *(const bf16x8*)(bbase + st + i * 32 * GS);
; #pragma unroll
;       for (int ks = 0; ks < 4; ++ks) {
;         if (ks + 1 < 4) {
; #pragma unroll
;           for (int i = 0; i < 4; ++i) fa[(ks + 1) & 1][i] = *(const bf16x8*)(abase + st + i * 32 * GS + (ks + 1) * 32);
; #pragma unroll
;           for (int i = 0; i < 2; ++i) fb[(ks + 1) & 1][i] = *(const bf16x8*)(bbase + st + i * 32 * GS + (ks + 1) * 32);
;         }
;         __builtin_amdgcn_sched_barrier(0);
;         __builtin_amdgcn_s_setprio(1);
; #pragma unroll
;         for (int mt = 0; mt < 4; ++mt)
; #pragma unroll
;           for (int nt = 0; nt < 2; ++nt)
;             acc[mt][nt] = SWAP ? MFMA32(fb[ks & 1][nt], fa[ks & 1][mt], acc[mt][nt]) : MFMA32(fa[ks & 1][mt], fb[ks & 1][nt], acc[mt][nt]);
;         __builtin_amdgcn_s_setprio(0);
;         __builtin_amdgcn_sched_barrier(0);
;       }
;     }
;     if (kt + 1 < nk) G_WRITE((kt + 1) & 1);
;     if (kt + 2 < nk) G_LOAD(kt + 2);
;     __syncthreads();
;   }
.LBB0_292:
	s_cmp_gt_u32 s86, 29
	s_cbranch_scc1 .Lg292_tail
	ds_read_b128 v[214:217], v240 offset:36864
	ds_read_b128 v[182:185], v177
	ds_read_b128 v[232:235], v240 offset:41472
	ds_read_b128 v[190:193], v177 offset:4608
	ds_read_b128 v[198:201], v177 offset:9216
	ds_read_b128 v[206:209], v177 offset:13824
	s_setprio 1
	s_waitcnt lgkmcnt(4)
	v_mfma_f32_32x32x16_bf16 v[114:129], v[214:217], v[182:185], v[114:129]
	ds_read_b128 v[218:221], v240 offset:36896
	s_waitcnt lgkmcnt(4)
	v_mfma_f32_32x32x16_bf16 v[98:113], v[232:235], v[182:185], v[98:113]
	ds_read_b128 v[186:189], v177 offset:32
	ds_read_b128 v[182:185], v177 offset:64
	s_waitcnt lgkmcnt(5)
	v_mfma_f32_32x32x16_bf16 v[82:97], v[214:217], v[190:193], v[82:97]
	ds_read_b128 v[236:239], v240 offset:41504
	v_mfma_f32_32x32x16_bf16 v[66:81], v[232:235], v[190:193], v[66:81]
	ds_read_b128 v[194:197], v177 offset:4640
	ds_read_b128 v[190:193], v177 offset:4672
	s_waitcnt lgkmcnt(7)
	v_mfma_f32_32x32x16_bf16 v[50:65], v[214:217], v[198:201], v[50:65]
	ds_read_b128 v[202:205], v177 offset:9248
	v_mfma_f32_32x32x16_bf16 v[34:49], v[232:235], v[198:201], v[34:49]
	ds_read_b128 v[210:213], v177 offset:13856
	ds_read_b128 v[198:201], v177 offset:9280
	s_waitcnt lgkmcnt(9)
	v_mfma_f32_32x32x16_bf16 v[18:33], v[214:217], v[206:209], v[18:33]
	ds_read_b128 v[214:217], v240 offset:36928
	v_mfma_f32_32x32x16_bf16 v[2:17], v[232:235], v[206:209], v[2:17]
	ds_read_b128 v[232:235], v240 offset:41536
	ds_read_b128 v[206:209], v177 offset:13888
	s_setprio 0
	s_setprio 1
	s_waitcnt lgkmcnt(10)
	v_mfma_f32_32x32x16_bf16 v[114:129], v[218:221], v[186:189], v[114:129]
	s_waitcnt lgkmcnt(8)
	v_mfma_f32_32x32x16_bf16 v[98:113], v[236:239], v[186:189], v[98:113]
	ds_read_b128 v[186:189], v177 offset:96
	s_waitcnt lgkmcnt(8)
	v_mfma_f32_32x32x16_bf16 v[82:97], v[218:221], v[194:197], v[82:97]
	v_mfma_f32_32x32x16_bf16 v[66:81], v[236:239], v[194:197], v[66:81]
	ds_read_b128 v[194:197], v177 offset:4704
	s_waitcnt lgkmcnt(7)
	v_mfma_f32_32x32x16_bf16 v[50:65], v[218:221], v[202:205], v[50:65]
	v_mfma_f32_32x32x16_bf16 v[34:49], v[236:239], v[202:205], v[34:49]
	ds_read_b128 v[202:205], v177 offset:9312
	s_waitcnt lgkmcnt(7)
	v_mfma_f32_32x32x16_bf16 v[18:33], v[218:221], v[210:213], v[18:33]
	ds_read_b128 v[218:221], v240 offset:36960
	v_mfma_f32_32x32x16_bf16 v[2:17], v[236:239], v[210:213], v[2:17]
	ds_read_b128 v[236:239], v240 offset:41568
	ds_read_b128 v[210:213], v177 offset:13920
	s_setprio 0
	s_setprio 1
	s_waitcnt lgkmcnt(8)
	v_mfma_f32_32x32x16_bf16 v[114:129], v[214:217], v[182:185], v[114:129]
	s_waitcnt lgkmcnt(7)
	v_mfma_f32_32x32x16_bf16 v[98:113], v[232:235], v[182:185], v[98:113]
	v_mfma_f32_32x32x16_bf16 v[82:97], v[214:217], v[190:193], v[82:97]
	v_mfma_f32_32x32x16_bf16 v[66:81], v[232:235], v[190:193], v[66:81]
	v_mfma_f32_32x32x16_bf16 v[50:65], v[214:217], v[198:201], v[50:65]
	v_mfma_f32_32x32x16_bf16 v[34:49], v[232:235], v[198:201], v[34:49]
	s_waitcnt lgkmcnt(6)
	v_mfma_f32_32x32x16_bf16 v[18:33], v[214:217], v[206:209], v[18:33]
	v_mfma_f32_32x32x16_bf16 v[2:17], v[232:235], v[206:209], v[2:17]
	s_setprio 0
	s_setprio 1
	s_and_b32 s4, s85, 2
	s_mul_i32 s4, s4, 0x9000
	v_add_u32_e32 v242, s4, v174
	v_lshl_add_u64 v[244:245], v[180:181], 0, s[82:83]
	v_lshl_add_u64 v[246:247], v[178:179], 0, s[82:83]
	s_waitcnt lgkmcnt(2)
	v_mfma_f32_32x32x16_bf16 v[114:129], v[218:221], v[186:189], v[114:129]
	s_waitcnt vmcnt(7)
	ds_write_b128 v242, v[130:133]
	global_load_dwordx4 v[130:133], v[244:245], off offset:256
	v_add_co_u32_e32 v244, vcc, 0x40000, v244
	s_waitcnt lgkmcnt(2)
	v_mfma_f32_32x32x16_bf16 v[98:113], v[236:239], v[186:189], v[98:113]
	s_waitcnt vmcnt(7)
	ds_write_b128 v242, v[134:137] offset:36864
	v_addc_co_u32_e32 v245, vcc, 0, v245, vcc
	global_load_dwordx4 v[134:137], v[246:247], off offset:256
	v_add_co_u32_e32 v246, vcc, 0x40000, v246
	v_mfma_f32_32x32x16_bf16 v[82:97], v[218:221], v[194:197], v[82:97]
	s_waitcnt vmcnt(7)
	ds_write_b128 v242, v[138:141] offset:9216
	v_addc_co_u32_e32 v247, vcc, 0, v247, vcc
	global_load_dwordx4 v[138:141], v[244:245], off offset:256
	v_add_co_u32_e32 v244, vcc, 0x40000, v244
	v_mfma_f32_32x32x16_bf16 v[66:81], v[236:239], v[194:197], v[66:81]
	s_waitcnt vmcnt(7)
	ds_write_b128 v242, v[142:145] offset:46080
	v_addc_co_u32_e32 v245, vcc, 0, v245, vcc
	global_load_dwordx4 v[142:145], v[246:247], off offset:256
	v_add_co_u32_e32 v246, vcc, 0x40000, v246
	v_mfma_f32_32x32x16_bf16 v[50:65], v[218:221], v[202:205], v[50:65]
	s_waitcnt vmcnt(7)
	ds_write_b128 v242, v[146:149] offset:18432
	v_addc_co_u32_e32 v247, vcc, 0, v247, vcc
	global_load_dwordx4 v[146:149], v[244:245], off offset:256
	v_add_co_u32_e32 v244, vcc, 0x40000, v244
	v_mfma_f32_32x32x16_bf16 v[34:49], v[236:239], v[202:205], v[34:49]
	s_waitcnt vmcnt(7)
	ds_write_b128 v242, v[150:153] offset:55296
	v_addc_co_u32_e32 v245, vcc, 0, v245, vcc
	global_load_dwordx4 v[150:153], v[246:247], off offset:256
	v_add_co_u32_e32 v246, vcc, 0x40000, v246
	s_waitcnt lgkmcnt(6)
	v_mfma_f32_32x32x16_bf16 v[18:33], v[218:221], v[210:213], v[18:33]
	s_waitcnt vmcnt(7)
	ds_write_b128 v242, v[154:157] offset:27648
	v_addc_co_u32_e32 v247, vcc, 0, v247, vcc
	global_load_dwordx4 v[154:157], v[244:245], off offset:256
	v_mfma_f32_32x32x16_bf16 v[2:17], v[236:239], v[210:213], v[2:17]
	s_waitcnt vmcnt(7)
	ds_write_b128 v242, v[158:161] offset:64512
	global_load_dwordx4 v[158:161], v[246:247], off offset:256
	s_setprio 0
	s_branch .LBB0_291
